# gemm_wide second k-step: ds_read fragment prefetch 3 deep using v244-v255 instead of serialized read-wait-mfma chain
# baseline (speedup 1.0000x reference)
; template <int EPI>
; __device__ __forceinline__ void gemm_wide(const WS& ws, const bf16_t* A, int lda, const bf16_t* __restrict__ W, int K, float invK,
;                                           int ntn, int ntiles, int bid) {
;     ...
;     auto issue = [&]() {
;       const int idc = l_id < last_id ? l_id : last_id;
;       int mt, nt; tile_of(idc, ntn, mt, nt);
;       const int arow = mt * 256 + hh * 128 + srow;
;       const bf16_t* akb = A + l_kt * 64 + (tid & 7) * 8;
;       const bf16_t* wp = W + (size_t)(nt * 256 + wrow) * K + l_kt * 64 + (tid5 & 7) * 8;
; #pragma unroll
;       for (int i = 0; i < 4; ++i) {
;         int r = arow + 32 * i; r = r < M_ ? r : M_ - 1;
;         ra[i] = *(const u32x4*)(akb + (size_t)r * lda);
;         rb[i] = *(const u32x4*)(wp + (size_t)i * 64 * K);
;       }
;       if (++l_kt == nk) { l_kt = 0; l_id += G; }
;     };
;     auto store = [&](int buf) {
; #pragma unroll
;       for (int i = 0; i < 4; ++i) {
;         ss[i] += sumsq8(__builtin_bit_cast(bf16x8, ra[i]));
;         *(u32x4*)(As + buf * 16384 + i * 4096 + soff) = ra[i];
;         *(u32x4*)(Bs + buf * 32768 + i * 8192 + woff) = rb[i];
;       }
;       if (++st_kt == nk) {
;         st_kt = 0;
; #pragma unroll
;         for (int i = 0; i < 4; ++i) {
;           float t = ss[i];
;           t += __shfl_xor(t, 1); t += __shfl_xor(t, 2); t += __shfl_xor(t, 4);
;           if ((tid & 7) == 0) rsl[srow + 32 * i] = rsqrtf(t * invK + EPS_);
;           ss[i] = 0.f;
;         }
;       }
;     };
;     auto compute = [&](int buf) {
;       const unsigned char* Ab = As + buf * 16384 + (wn * 64 + lr) * 128;
;       const unsigned char* Bb = Bs + buf * 32768 + (wm * 64 + lr) * 128;
; #pragma unroll
;       for (int ks = 0; ks < 2; ++ks) {
;         if (ks == 1) __builtin_amdgcn_sched_barrier(0);
;         const int sw = ((ks * 4 + lq) ^ (lr & 7)) << 4;
;         bf16x8 xf[4], wf[4];
; #pragma unroll
;         for (int i = 0; i < 4; ++i) { xf[i] = *(const bf16x8*)(Ab + i * 2048 + sw); wf[i] = *(const bf16x8*)(Bb + i * 2048 + sw); }
; #pragma unroll
;         for (int ni = 0; ni < 4; ++ni)
; #pragma unroll
;           for (int ti = 0; ti < 4; ++ti) accA[ni][ti] = MFMA16(wf[ni], xf[ti], accA[ni][ti]);
; #pragma unroll
;         for (int i = 0; i < 4; ++i) wf[i] = *(const bf16x8*)(Bb + 16384 + i * 2048 + sw);
; #pragma unroll
;         for (int ni = 0; ni < 4; ++ni)
.LBB0_1043:
	s_and_b32 s5, s35, 1
	v_lshl_add_u32 v13, s5, 15, v206
	v_add_u32_e32 v134, v13, v207
	ds_read_b128 v[98:101], v134
	v_lshl_add_u32 v226, s5, 14, v205
	v_add_u32_e32 v118, v226, v207
	ds_read_b128 v[102:105], v118
	ds_read_b128 v[110:113], v118 offset:2048
	ds_read_b128 v[106:109], v134 offset:2048
	ds_read_b128 v[178:181], v118 offset:4096
	ds_read_b128 v[182:185], v118 offset:6144
	s_waitcnt lgkmcnt(2)
	v_mfma_f32_16x16x32_bf16 v[142:145], v[106:109], v[102:105], v[142:145]
	v_lshl_add_u32 v118, s7, 8, v201
	v_add_u32_e32 v224, s4, v202
	s_lshl_b32 s4, s65, 6
	v_mfma_f32_16x16x32_bf16 v[158:161], v[98:101], v[102:105], v[158:161]
	v_ashrrev_i32_e32 v119, 31, v118
	s_ashr_i32 s5, s4, 31
	s_lshl_b64 s[4:5], s[4:5], 1
	v_mfma_f32_16x16x32_bf16 v[154:157], v[98:101], v[110:113], v[154:157]
	v_mov_b32_e32 v169, v12
	v_lshl_add_u64 v[220:221], v[162:163], 0, s[4:5]
	s_mov_b32 s3, 0x20000
	s_waitcnt lgkmcnt(1)
	v_mfma_f32_16x16x32_bf16 v[150:153], v[98:101], v[178:181], v[150:153]
	s_mov_b32 s2, 0x20000
	s_waitcnt lgkmcnt(0)
	v_mfma_f32_16x16x32_bf16 v[146:149], v[98:101], v[182:185], v[146:149]
	v_mfma_f32_16x16x32_bf16 v[138:141], v[106:109], v[110:113], v[138:141]
	v_mfma_f32_16x16x32_bf16 v[130:133], v[106:109], v[178:181], v[130:133]
	v_mfma_f32_16x16x32_bf16 v[114:117], v[106:109], v[182:185], v[114:117]
	ds_read_b128 v[98:101], v134 offset:4096
	ds_read_b128 v[106:109], v134 offset:6144
	ds_read_b128 v[122:125], v134 offset:18432
	s_waitcnt lgkmcnt(2)
	v_mfma_f32_16x16x32_bf16 v[94:97], v[98:101], v[102:105], v[94:97]
	v_mfma_f32_16x16x32_bf16 v[90:93], v[98:101], v[110:113], v[90:93]
	v_mfma_f32_16x16x32_bf16 v[86:89], v[98:101], v[178:181], v[86:89]
	v_mfma_f32_16x16x32_bf16 v[82:85], v[98:101], v[182:185], v[82:85]
	ds_read_b128 v[98:101], v134 offset:16384
	s_waitcnt lgkmcnt(2)
	v_mfma_f32_16x16x32_bf16 v[78:81], v[106:109], v[102:105], v[78:81]
	v_mfma_f32_16x16x32_bf16 v[74:77], v[106:109], v[110:113], v[74:77]
	v_mfma_f32_16x16x32_bf16 v[70:73], v[106:109], v[178:181], v[70:73]
	v_mfma_f32_16x16x32_bf16 v[66:69], v[106:109], v[182:185], v[66:69]
	v_lshlrev_b64 v[106:107], 11, v[118:119]
	v_lshl_add_u64 v[106:107], s[48:49], 0, v[106:107]
	v_lshl_add_u64 v[106:107], v[106:107], 0, s[4:5]
	v_min_i32_e32 v108, 0x405f, v224
	v_lshl_add_u64 v[222:223], v[106:107], 0, v[168:169]
	v_min_i32_e32 v106, 0x407f, v224
	v_ashrrev_i32_e32 v109, 31, v108
	s_waitcnt lgkmcnt(0)
	v_mfma_f32_16x16x32_bf16 v[62:65], v[98:101], v[102:105], v[62:65]
	v_ashrrev_i32_e32 v107, 31, v106
	v_lshlrev_b64 v[106:107], 11, v[106:107]
	v_lshl_add_u64 v[106:107], v[220:221], 0, v[106:107]
	v_mfma_f32_16x16x32_bf16 v[58:61], v[98:101], v[110:113], v[58:61]
	global_load_dwordx4 v[126:129], v[222:223], off
	v_mfma_f32_16x16x32_bf16 v[54:57], v[98:101], v[178:181], v[54:57]
	v_mfma_f32_16x16x32_bf16 v[50:53], v[98:101], v[182:185], v[50:53]
	v_lshlrev_b64 v[98:99], 11, v[108:109]
	v_lshl_add_u64 v[98:99], v[220:221], 0, v[98:99]
	v_add_co_u32_e32 v98, vcc, s82, v98
	v_mfma_f32_16x16x32_bf16 v[46:49], v[122:125], v[102:105], v[46:49]
	s_nop 0
	v_addc_co_u32_e32 v99, vcc, 0, v99, vcc
	global_load_dwordx4 v[118:121], v[106:107], off
	s_nop 0
	global_load_dwordx4 v[106:109], v[98:99], off
	ds_read_b128 v[212:215], v134 offset:20480
	ds_read_b128 v[216:219], v134 offset:22528
	v_add_co_u32_e32 v98, vcc, s3, v222
	v_mfma_f32_16x16x32_bf16 v[42:45], v[122:125], v[110:113], v[42:45]
	s_nop 0
	v_addc_co_u32_e32 v99, vcc, 0, v223, vcc
	v_mfma_f32_16x16x32_bf16 v[38:41], v[122:125], v[178:181], v[38:41]
	v_mfma_f32_16x16x32_bf16 v[34:37], v[122:125], v[182:185], v[34:37]
	global_load_dwordx4 v[122:125], v[98:99], off
	v_min_i32_e32 v98, 0x403f, v224
	v_ashrrev_i32_e32 v99, 31, v98
	v_lshlrev_b64 v[98:99], 11, v[98:99]
	v_lshl_add_u64 v[98:99], v[220:221], 0, v[98:99]
	v_add_co_u32_e32 v98, vcc, s3, v98
	v_min_i32_e32 v224, 0x401f, v224
	s_nop 0
	v_addc_co_u32_e32 v99, vcc, 0, v99, vcc
	s_mov_b32 s3, 0x40000
	v_ashrrev_i32_e32 v225, 31, v224
	s_waitcnt lgkmcnt(1)
; #define MFMA16(a, b, c) __builtin_amdgcn_mfma_f32_16x16x32_bf16((a), (b), (c), 0, 0, 0)
; template <int EPI>
; __device__ __forceinline__ void gemm_wide(const WS& ws, const bf16_t* A, int lda, const bf16_t* __restrict__ W, int K, float invK,
;                                           int ntn, int ntiles, int bid) {
;     ...
;       for (int ks = 0; ks < 2; ++ks) {
;         if (ks == 1) __builtin_amdgcn_sched_barrier(0);
;         const int sw = ((ks * 4 + lq) ^ (lr & 7)) << 4;
;         bf16x8 xf[4], wf[4];
; #pragma unroll
;         for (int i = 0; i < 4; ++i) { xf[i] = *(const bf16x8*)(Ab + i * 2048 + sw); wf[i] = *(const bf16x8*)(Bb + i * 2048 + sw); }
; #pragma unroll
;         for (int ni = 0; ni < 4; ++ni)
; #pragma unroll
;           for (int ti = 0; ti < 4; ++ti) accA[ni][ti] = MFMA16(wf[ni], xf[ti], accA[ni][ti]);
; #pragma unroll
;         for (int i = 0; i < 4; ++i) wf[i] = *(const bf16x8*)(Bb + 16384 + i * 2048 + sw);
; #pragma unroll
;         for (int ni = 0; ni < 4; ++ni)
; #pragma unroll
;           for (int ti = 0; ti < 4; ++ti) accB[ni][ti] = MFMA16(wf[ni], xf[ti], accB[ni][ti]);
;       }
;     };
;     auto tile_end = [&]() {
;       float rs[4];
; #pragma unroll
;       for (int ti = 0; ti < 4; ++ti) rs[ti] = rsl[wn * 64 + ti * 16 + lr];
;       int mt, nt; tile_of(c_id, ntn, mt, nt);
	v_mfma_f32_16x16x32_bf16 v[30:33], v[212:215], v[102:105], v[30:33]
	v_add_co_u32_e32 v134, vcc, s3, v222
	s_mov_b32 s3, 0x30000
	v_mfma_f32_16x16x32_bf16 v[26:29], v[212:215], v[110:113], v[26:29]
	v_addc_co_u32_e32 v135, vcc, 0, v223, vcc
	global_load_dwordx4 v[98:101], v[98:99], off
	v_mfma_f32_16x16x32_bf16 v[22:25], v[212:215], v[178:181], v[22:25]
	global_load_dwordx4 v[134:137], v[134:135], off
	v_mfma_f32_16x16x32_bf16 v[18:21], v[212:215], v[182:185], v[18:21]
	v_lshlrev_b64 v[212:213], 11, v[224:225]
	v_lshl_add_u64 v[212:213], v[220:221], 0, v[212:213]
	s_waitcnt lgkmcnt(0)
	v_mfma_f32_16x16x32_bf16 v[14:17], v[216:219], v[102:105], v[14:17]
	v_add_co_u32_e32 v102, vcc, s3, v212
	s_mov_b32 s3, 0x60000
	s_nop 0
	v_addc_co_u32_e32 v103, vcc, 0, v213, vcc
	v_mfma_f32_16x16x32_bf16 v[8:11], v[216:219], v[110:113], v[8:11]
	v_add_co_u32_e32 v110, vcc, s3, v222
	global_load_dwordx4 v[102:105], v[102:103], off
	s_nop 0
	v_addc_co_u32_e32 v111, vcc, 0, v223, vcc
	global_load_dwordx4 v[110:113], v[110:111], off
	v_mfma_f32_16x16x32_bf16 v[4:7], v[216:219], v[178:181], v[4:7]
	v_mfma_f32_16x16x32_bf16 v[0:3], v[216:219], v[182:185], v[0:3]
	v_add_u32_e32 v13, v13, v208
	ds_read_b128 v[178:181], v13
	v_add_u32_e32 v169, v226, v208
	ds_read_b128 v[182:185], v169
	ds_read_b128 v[212:215], v169 offset:2048
	ds_read_b128 v[216:219], v169 offset:4096
	ds_read_b128 v[220:223], v169 offset:6144
	ds_read_b128 v[244:247], v13 offset:2048
	ds_read_b128 v[248:251], v13 offset:4096
	ds_read_b128 v[252:255], v13 offset:6144
	s_add_i32 s6, s6, 1
	s_waitcnt lgkmcnt(6)
	v_mfma_f32_16x16x32_bf16 v[158:161], v[178:181], v[182:185], v[158:161]
	s_waitcnt lgkmcnt(5)
	v_mfma_f32_16x16x32_bf16 v[154:157], v[178:181], v[212:215], v[154:157]
	s_waitcnt lgkmcnt(4)
	v_mfma_f32_16x16x32_bf16 v[150:153], v[178:181], v[216:219], v[150:153]
	s_waitcnt lgkmcnt(3)
	v_mfma_f32_16x16x32_bf16 v[146:149], v[178:181], v[220:223], v[146:149]
	ds_read_b128 v[178:181], v13 offset:16384
	s_waitcnt lgkmcnt(3)
	v_mfma_f32_16x16x32_bf16 v[142:145], v[244:247], v[182:185], v[142:145]
	v_mfma_f32_16x16x32_bf16 v[138:141], v[244:247], v[212:215], v[138:141]
	v_mfma_f32_16x16x32_bf16 v[130:133], v[244:247], v[216:219], v[130:133]
	v_mfma_f32_16x16x32_bf16 v[114:117], v[244:247], v[220:223], v[114:117]
	ds_read_b128 v[244:247], v13 offset:18432
	s_waitcnt lgkmcnt(3)
	v_mfma_f32_16x16x32_bf16 v[94:97], v[248:251], v[182:185], v[94:97]
	v_mfma_f32_16x16x32_bf16 v[90:93], v[248:251], v[212:215], v[90:93]
	v_mfma_f32_16x16x32_bf16 v[86:89], v[248:251], v[216:219], v[86:89]
	v_mfma_f32_16x16x32_bf16 v[82:85], v[248:251], v[220:223], v[82:85]
	ds_read_b128 v[248:251], v13 offset:20480
	s_waitcnt lgkmcnt(3)
	v_mfma_f32_16x16x32_bf16 v[78:81], v[252:255], v[182:185], v[78:81]
	v_mfma_f32_16x16x32_bf16 v[74:77], v[252:255], v[212:215], v[74:77]
	v_mfma_f32_16x16x32_bf16 v[70:73], v[252:255], v[216:219], v[70:73]
	v_mfma_f32_16x16x32_bf16 v[66:69], v[252:255], v[220:223], v[66:69]
	ds_read_b128 v[252:255], v13 offset:22528
	s_waitcnt lgkmcnt(3)
	v_mfma_f32_16x16x32_bf16 v[62:65], v[178:181], v[182:185], v[62:65]
	v_mfma_f32_16x16x32_bf16 v[58:61], v[178:181], v[212:215], v[58:61]
	v_mfma_f32_16x16x32_bf16 v[54:57], v[178:181], v[216:219], v[54:57]
	v_mfma_f32_16x16x32_bf16 v[50:53], v[178:181], v[220:223], v[50:53]
	s_waitcnt lgkmcnt(2)
	v_mfma_f32_16x16x32_bf16 v[46:49], v[244:247], v[182:185], v[46:49]
	v_mfma_f32_16x16x32_bf16 v[42:45], v[244:247], v[212:215], v[42:45]
	v_mfma_f32_16x16x32_bf16 v[38:41], v[244:247], v[216:219], v[38:41]
	v_mfma_f32_16x16x32_bf16 v[34:37], v[244:247], v[220:223], v[34:37]
	s_waitcnt lgkmcnt(1)
	v_mfma_f32_16x16x32_bf16 v[30:33], v[248:251], v[182:185], v[30:33]
	v_mfma_f32_16x16x32_bf16 v[26:29], v[248:251], v[212:215], v[26:29]
	v_mfma_f32_16x16x32_bf16 v[22:25], v[248:251], v[216:219], v[22:25]
	v_mfma_f32_16x16x32_bf16 v[18:21], v[248:251], v[220:223], v[18:21]
	s_waitcnt lgkmcnt(0)
	v_mfma_f32_16x16x32_bf16 v[14:17], v[252:255], v[182:185], v[14:17]
	v_mfma_f32_16x16x32_bf16 v[8:11], v[252:255], v[212:215], v[8:11]
	v_mfma_f32_16x16x32_bf16 v[4:7], v[252:255], v[216:219], v[4:7]
	v_mfma_f32_16x16x32_bf16 v[0:3], v[252:255], v[220:223], v[0:3]
	s_cmp_lg_u32 s6, 16
	s_cbranch_scc1 .LBB0_1094
	ds_read2_b32 v[180:181], v210 offset1:16
	ds_read2_b32 v[178:179], v210 offset0:32 offset1:48
	s_cmpk_gt_i32 s62, 0x4ff
	s_mov_b64 s[4:5], -1
	s_cbranch_scc0 .LBB0_1047
	s_add_i32 s7, s62, 0xfffffb00
	s_movk_i32 s4, 0x4000
	s_cbranch_execz .LBB0_1048

; __global__ void __launch_bounds__(512, 2) fwd_megakernel(Params p) {
	.amdhsa_kernel _Z14fwd_megakernel6Params
		.amdhsa_group_segment_fixed_size 151568
		.amdhsa_private_segment_fixed_size 0
		.amdhsa_kernarg_size 528
		.amdhsa_user_sgpr_count 2
		.amdhsa_user_sgpr_dispatch_ptr 0
		.amdhsa_user_sgpr_queue_ptr 0
		.amdhsa_user_sgpr_kernarg_segment_ptr 1
		.amdhsa_user_sgpr_dispatch_id 0
		.amdhsa_user_sgpr_kernarg_preload_length 0
		.amdhsa_user_sgpr_kernarg_preload_offset 0
		.amdhsa_user_sgpr_private_segment_size 0
		.amdhsa_uses_dynamic_stack 0
		.amdhsa_enable_private_segment 0
		.amdhsa_system_sgpr_workgroup_id_x 1
		.amdhsa_system_sgpr_workgroup_id_y 0
		.amdhsa_system_sgpr_workgroup_id_z 0
		.amdhsa_system_sgpr_workgroup_info 0
		.amdhsa_system_vgpr_workitem_id 2
		.amdhsa_next_free_vgpr 256
		.amdhsa_next_free_sgpr 100
		.amdhsa_accum_offset 256
		.amdhsa_reserve_vcc 1
		.amdhsa_float_round_mode_32 0
		.amdhsa_float_round_mode_16_64 0
		.amdhsa_float_denorm_mode_32 3
		.amdhsa_float_denorm_mode_16_64 3
		.amdhsa_dx10_clamp 1
		.amdhsa_ieee_mode 1
		.amdhsa_fp16_overflow 0
		.amdhsa_tg_split 0
		.amdhsa_exception_fp_ieee_invalid_op 0
		.amdhsa_exception_fp_denorm_src 0
		.amdhsa_exception_fp_ieee_div_zero 0
		.amdhsa_exception_fp_ieee_overflow 0
		.amdhsa_exception_fp_ieee_underflow 0
		.amdhsa_exception_fp_ieee_inexact 0
		.amdhsa_exception_int_div_zero 0
	.end_amdhsa_kernel

; __global__ void __launch_bounds__(512, 2) fwd_megakernel(Params p) {
amdhsa.kernels:
  - .agpr_count:     0
    .args:
      - .offset:         0
        .size:           272
        .value_kind:     by_value
      - .offset:         272
        .size:           4
        .value_kind:     hidden_block_count_x
      - .offset:         276
        .size:           4
        .value_kind:     hidden_block_count_y
      - .offset:         280
        .size:           4
        .value_kind:     hidden_block_count_z
      - .offset:         284
        .size:           2
        .value_kind:     hidden_group_size_x
      - .offset:         286
        .size:           2
        .value_kind:     hidden_group_size_y
      - .offset:         288
        .size:           2
        .value_kind:     hidden_group_size_z
      - .offset:         290
        .size:           2
        .value_kind:     hidden_remainder_x
      - .offset:         292
        .size:           2
        .value_kind:     hidden_remainder_y
      - .offset:         294
        .size:           2
        .value_kind:     hidden_remainder_z
      - .offset:         312
        .size:           8
        .value_kind:     hidden_global_offset_x
      - .offset:         320
        .size:           8
        .value_kind:     hidden_global_offset_y
      - .offset:         328
        .size:           8
        .value_kind:     hidden_global_offset_z
      - .offset:         336
        .size:           2
        .value_kind:     hidden_grid_dims
      - .offset:         360
        .size:           8
        .value_kind:     hidden_multigrid_sync_arg
    .group_segment_fixed_size: 151568
    .kernarg_segment_align: 8
    .kernarg_segment_size: 528
    .language:       OpenCL C
    .language_version:
      - 2
      - 0
    .max_flat_workgroup_size: 512
    .name:           _Z14fwd_megakernel6Params
    .private_segment_fixed_size: 0
    .sgpr_count:     106
    .sgpr_spill_count: 96
    .symbol:         _Z14fwd_megakernel6Params.kd
    .uniform_work_group_size: 1
    .uses_dynamic_stack: false
    .vgpr_count:     256
    .vgpr_spill_count: 0
    .wavefront_size: 64
